# baseline (speedup 1.0000x reference)
.LBB0_34:
	s_or_b64 exec, exec, s[0:1]
	v_mov_b32_e32 v129, 0
	s_waitcnt lgkmcnt(0)
	s_barrier
	ds_read_b96 v[0:2], v129
	s_add_u32 s56, s38, 0x16000000
	s_addc_u32 s57, s39, 0
	s_mov_b32 s67, 0
	s_mov_b32 s35, s67
	s_waitcnt lgkmcnt(0)
	v_readfirstlane_b32 s1, v1
	v_readfirstlane_b32 s0, v0
	s_movk_i32 s33, 0x80
	v_writelane_b32 v254, s1, 5
	v_readfirstlane_b32 s1, v2
	s_movk_i32 s48, 0x110
	s_movk_i32 s49, 0x210
	v_writelane_b32 v254, s1, 6
	s_add_u32 s1, s38, 0x6000000
	v_writelane_b32 v254, s1, 7
	s_addc_u32 s1, s39, 0
	s_add_u32 s2, s38, 0x27000000
	v_writelane_b32 v254, s1, 8
	s_addc_u32 s3, s39, 0
	v_writelane_b32 v254, s2, 9
	s_add_u32 s1, s38, 0xe000000
	v_mov_b32_e32 v149, 1
	v_writelane_b32 v254, s3, 10
	v_writelane_b32 v254, s1, 11
	s_addc_u32 s1, s39, 0
	s_add_u32 s2, s38, 0x18000000
	v_writelane_b32 v254, s1, 12
	s_addc_u32 s3, s39, 0
	v_writelane_b32 v254, s2, 13
	s_add_u32 s1, s38, 0x30815000
	v_mov_b32_e32 v154, 0x42800000
	v_writelane_b32 v254, s3, 14
	v_writelane_b32 v254, s1, 15
	s_addc_u32 s1, s39, 0
	v_writelane_b32 v254, s1, 16
	s_add_u32 s1, s38, 0x30814000
	v_writelane_b32 v254, s1, 17
	s_addc_u32 s1, s39, 0
	s_add_u32 s2, s38, 0x25000000
	v_writelane_b32 v254, s1, 18
	s_addc_u32 s3, s39, 0
	v_writelane_b32 v254, s2, 19
	s_add_u32 s1, s38, 0x4000000
	v_mov_b32_e32 v152, 0xf149f2ca
	v_writelane_b32 v254, s3, 20
	v_writelane_b32 v254, s1, 21
	s_addc_u32 s1, s39, 0
	s_add_u32 s2, s38, 0x20000000
	v_writelane_b32 v254, s1, 22
	s_addc_u32 s3, s39, 0
	v_writelane_b32 v254, s2, 23
	s_add_u32 s1, s38, 0x23000000
	v_mov_b32_e32 v153, 0x7149f2ca
	v_writelane_b32 v254, s3, 24
	v_writelane_b32 v254, s1, 25
	s_addc_u32 s1, s39, 0
	v_writelane_b32 v254, s1, 26
	s_add_u32 s1, s38, 0x2f400000
	v_writelane_b32 v254, s1, 27
	s_addc_u32 s1, s39, 0
	v_writelane_b32 v254, s1, 28
	s_add_u32 s1, s38, 0x30410000
	v_writelane_b32 v254, s1, 29
	s_addc_u32 s1, s39, 0
	s_add_u32 s2, s38, 0x2fc10000
	v_writelane_b32 v254, s1, 30
	s_addc_u32 s3, s39, 0
	v_writelane_b32 v254, s2, 31
	s_add_u32 s1, s38, 0x2fc00000
	v_bfrev_b32_e32 v155, 0.5
	v_writelane_b32 v254, s3, 32
	v_writelane_b32 v254, s1, 33
	s_addc_u32 s1, s39, 0
	s_add_u32 s2, s38, 0x2f000000
	v_writelane_b32 v254, s1, 34
	s_addc_u32 s3, s39, 0
	v_writelane_b32 v254, s2, 35
	s_add_u32 s1, s38, 0x3000000
	v_mov_b32_e32 v156, 0x13000
	v_writelane_b32 v254, s3, 36
	v_writelane_b32 v254, s1, 37
	s_addc_u32 s1, s39, 0
	s_add_u32 s2, s38, 0x2000000
	v_writelane_b32 v254, s1, 38
	s_addc_u32 s3, s39, 0
	v_writelane_b32 v254, s2, 39
	s_add_u32 s1, s38, 0x1800000
	s_mov_b32 s82, 0
	v_writelane_b32 v254, s3, 40
	v_writelane_b32 v254, s1, 41
	s_addc_u32 s1, s39, 0
	v_writelane_b32 v254, s1, 42
	s_movk_i32 s2, 0xf480
	v_readlane_b32 s3, v254, 0
	s_cmpk_lt_i32 s3, 0x1a00
	s_cselect_b64 s[4:5], -1, 0
	v_writelane_b32 v254, s4, 43
	s_cmpk_gt_i32 s3, 0xaff
	s_mov_b64 s[72:73], 0x80
	v_writelane_b32 v254, s5, 44
	s_cselect_b64 s[4:5], -1, 0
	v_writelane_b32 v254, s4, 45
	s_cmpk_gt_u32 s3, 0x127f
	s_mov_b32 s74, 0x3e0293ee
	v_writelane_b32 v254, s5, 46
	s_cselect_b64 s[4:5], -1, 0
	v_writelane_b32 v254, s4, 47
	s_cmpk_lt_u32 s3, 0x1700
	s_mov_b64 s[76:77], 0x100
	v_writelane_b32 v254, s5, 48
	s_cselect_b64 s[4:5], -1, 0
	s_add_i32 s1, s3, 0xfffff880
	s_lshl_b32 s0, s0, 6
	v_writelane_b32 v254, s1, 49
	s_add_i32 s34, s0, 0x500
	v_writelane_b32 v254, s34, 50
	s_addk_i32 s0, 0x900
	s_mov_b32 s1, s67
	v_writelane_b32 v254, s35, 51
	v_writelane_b32 v254, s0, 52
	s_mov_b64 s[78:79], 0x180
	s_mov_b32 s80, 0x3fd744fd
	v_writelane_b32 v254, s1, 53
	s_and_b64 s[0:1], s[4:5], exec
	s_cselect_b32 s0, s2, 0xfffff000
	s_add_i32 s0, s3, s0
	v_writelane_b32 v254, s0, 54
	v_writelane_b32 v254, s4, 55
	s_and_b64 s[0:1], s[4:5], exec
	s_cselect_b32 s0, 2, 3
	v_writelane_b32 v254, s5, 56
	v_writelane_b32 v254, s0, 57
	s_lshl_b32 s81, s6, 6
	s_lshl_b32 s75, s6, 8
	v_writelane_b32 v254, s1, 58
	s_lshl_b32 s0, s3, 6
	v_writelane_b32 v254, s0, 59
	s_lshl_b32 s0, s3, 8
	v_writelane_b32 v254, s0, 60
	s_lshl_b32 s0, s3, 4
	v_writelane_b32 v254, s0, 61
	s_add_i32 s0, s3, 0x100
	v_writelane_b32 v254, s0, 62
	s_add_i32 s0, s3, s6
	v_writelane_b32 v254, s0, 63
	s_mov_b32 s0, 0
	s_lshl_b32 s7, s6, 4
	v_writelane_b32 v255, s0, 0
	s_barrier
	s_branch .LBB0_38

.LBB0_60:
	v_readlane_b32 s0, v255, 1
	v_readlane_b32 s1, v255, 2
	s_and_b64 vcc, exec, s[0:1]
	s_cbranch_vccz .LBB0_445
	s_add_i32 s2, s82, -1
	s_and_b32 s0, s2, 7
	s_cmp_eq_u32 s0, 0
	s_cselect_b64 s[0:1], -1, 0
	s_cmp_lt_u32 s82, 24
	s_cselect_b64 s[4:5], -1, 0
	s_and_b64 s[0:1], s[0:1], s[4:5]
	s_andn2_b64 vcc, exec, s[0:1]
	s_cbranch_vccnz .LBB0_582
	s_cmp_eq_u32 s2, 0
	s_cselect_b64 s[0:1], -1, 0
	s_and_b64 s[4:5], s[0:1], exec
	s_movk_i32 s3, 0xc0
	s_cselect_b32 s44, s3, 0x80
	v_readlane_b32 s3, v254, 0
	s_cmp_lt_i32 s3, s44
	s_cbranch_scc1 .LBB0_582
	v_readlane_b32 s3, v254, 0
	s_sub_i32 s45, s3, s44
	s_and_b64 s[0:1], s[0:1], exec
	s_movk_i32 s0, 0x700
	s_cselect_b32 s46, 0x380, s0
	s_cmp_ge_i32 s45, s46
	s_cbranch_scc1 .LBB0_582
	s_lshr_b32 s2, s2, 3
	s_mul_i32 s3, s2, 7
	s_getpc_b64 s[0:1]
	s_add_u32 s0, s0, __const._Z10cv_set_segiiRiS_.tbl@rel32@lo+4
	s_addc_u32 s1, s1, __const._Z10cv_set_segiiRiS_.tbl@rel32@hi+12
	s_add_u32 s4, s0, s3
	s_addc_u32 s5, s1, 0
	v_mov_b32_e32 v0, v148
	s_getpc_b64 s[0:1]
	s_add_u32 s0, s0, __const._Z10cv_set_segiiRiS_.tbl@rel32@lo+11
	s_addc_u32 s1, s1, __const._Z10cv_set_segiiRiS_.tbl@rel32@hi+19
	v_mov_b32_e32 v1, s3
	global_load_ubyte v1, v1, s[0:1]
	s_movk_i32 s34, 0x180
	s_waitcnt vmcnt(0)
	v_readfirstlane_b32 s3, v1
	s_lshr_b32 s52, s3, 2
	s_cmp_lt_i32 s52, 1
	s_cbranch_scc1 .LBB0_69
	s_cmp_eq_u32 s52, 1
	s_mov_b64 s[0:1], -1
	s_cbranch_scc1 .LBB0_67
	s_and_b32 s0, s3, 0xf8
	s_cmp_eq_u32 s52, 4
	s_movk_i32 s1, 0x400
	s_cselect_b32 s1, 0x100, s1
	s_cmp_lg_u32 s0, 8
	s_cselect_b32 s34, s1, 0x80
	s_mov_b64 s[0:1], 0

.LBB0_661:
	s_add_i32 s47, s47, s6
	s_cmpk_lt_i32 s46, 0x1a00
	s_cselect_b64 s[40:41], -1, 0
	s_cmpk_gt_i32 s46, 0x19ff
	s_cbranch_scc1 .LBB0_670
	s_cmpk_lt_i32 s46, 0xb00
	s_cbranch_scc1 .LBB0_671
	s_cmpk_gt_u32 s46, 0x127f
	s_mov_b64 s[42:43], -1
	s_cbranch_scc0 .LBB0_668
	s_cmpk_gt_u32 s46, 0x16ff
	s_mov_b64 s[34:35], -1
	s_cbranch_scc0 .LBB0_666
	s_add_i32 s54, s46, 0xfffff000
	s_mov_b64 s[34:35], 0
.LBB0_666:
	s_mov_b64 s[42:43], 0
	s_mov_b64 s[2:3], 3
	s_andn2_b64 vcc, exec, s[34:35]
	s_mov_b64 s[34:35], 0
	s_cbranch_vccnz .LBB0_668
	s_add_i32 s54, s47, 0xfffff480
	s_mov_b64 s[34:35], -1
	s_mov_b64 s[2:3], 2
.LBB0_668:
	s_andn2_b64 vcc, exec, s[42:43]
	s_mov_b64 s[42:43], s[34:35]
	s_cbranch_vccnz .LBB0_672
	s_add_i32 s54, s47, 0xfffff880
	s_mov_b64 s[42:43], -1
	s_mov_b64 s[34:35], 0
	s_mov_b64 s[2:3], 1
	s_branch .LBB0_672
